# down GEMM tile order: 4x8 tile groups per XCD round (WGM 8->4) so the act rows of a group are reused from MALL in consecutive rounds instead of re-streamed from HBM
# speedup vs baseline: 1.0073x; 1.0017x over previous
;     __host__ __device__ bool next(int i, Unit& u) const {
;     ...
;         int wgid = (int)L; { const int q = nwg / NXCD, r = nwg % NXCD, xcd = wgid % NXCD, off = wgid / NXCD; wgid = (xcd < r ? xcd * (q + 1) : r * (q + 1) + (xcd - r) * q) + off; }
;         const int nig = WGM * nN, gid = wgid / nig, fm = gid * WGM, gsz = (nM - fm) < WGM ? (nM - fm) : WGM;
;         u.pm = fm + ((wgid % nig) % gsz); u.pn = (wgid % nig) / gsz; return true;
.LBB0_944:
	s_add_i32 s4, s8, s4
	s_lshr_b32 s7, s4, 6
	s_and_b32 s5, s4, 63
	s_lshl_b32 s7, s7, 2
	s_and_b32 s8, s5, 3
	s_waitcnt lgkmcnt(0)
	s_add_i32 s48, s7, s8
	s_lshr_b32 s49, s5, 2

;     __host__ __device__ bool next(int i, Unit& u) const {
;         const long L = (long)i * G + c; if (L >= nwg) return false;
;         int wgid = (int)L; { const int q = nwg / NXCD, r = nwg % NXCD, xcd = wgid % NXCD, off = wgid / NXCD; wgid = (xcd < r ? xcd * (q + 1) : r * (q + 1) + (xcd - r) * q) + off; }
;         const int nig = WGM * nN, gid = wgid / nig, fm = gid * WGM, gsz = (nM - fm) < WGM ? (nM - fm) : WGM;
;         u.pm = fm + ((wgid % nig) % gsz); u.pn = (wgid % nig) / gsz; return true;
.LBB0_956:
	s_ashr_i32 s4, s20, 3
	s_add_i32 s4, s26, s4
	s_lshr_b32 s20, s4, 6
	s_and_b32 s5, s4, 63
	s_lshl_b32 s20, s20, 2
	s_and_b32 s21, s5, 3
	s_add_i32 s47, s20, s21
	s_lshr_b32 s45, s5, 2
